# ret_out tail store scratch moved to LDS offset 0x3000 (outside the mask-word region of a following attention item); otherwise v33
# baseline (speedup 1.0000x reference)
.LBB0_871:
	s_or_b64 exec, exec, s[0:1]
	v_lshlrev_b32_e32 v15, 7, v169
	v_lshlrev_b64 v[16:17], 1, v[174:175]
	v_or_b32_e32 v14, v171, v192
	s_waitcnt lgkmcnt(0)
	v_lshl_add_u64 v[12:13], s[10:11], 0, v[16:17]
	v_lshlrev_b32_e32 v0, 1, v15
	v_lshlrev_b32_e32 v30, 2, v15
	v_ashrrev_i32_e32 v15, 31, v14
	v_lshl_add_u64 v[12:13], v[12:13], 0, v[0:1]
	v_lshlrev_b64 v[52:53], 1, v[14:15]
	v_lshl_add_u64 v[56:57], v[12:13], 0, v[52:53]
	s_barrier
	global_load_dwordx2 v[64:65], v[56:57], off
	v_mov_b32_e32 v31, v1
	v_lshl_add_u64 v[30:31], s[68:69], 0, v[30:31]
	v_lshl_add_u64 v[60:61], v[14:15], 2, v[30:31]
	global_load_dwordx4 v[12:15], v[60:61], off
	global_load_dwordx2 v[72:73], v[56:57], off offset:16
	global_load_dwordx4 v[30:33], v[60:61], off offset:32
	global_load_dwordx2 v[74:75], v[56:57], off offset:32
	global_load_dwordx4 v[40:43], v[60:61], off offset:64
	global_load_dwordx2 v[76:77], v[56:57], off offset:48
	global_load_dwordx4 v[44:47], v[60:61], off offset:96
	global_load_dwordx2 v[78:79], v[56:57], off offset:64
	global_load_dwordx4 v[48:51], v[60:61], off offset:128
	v_xor_b32_e32 v10, 64, v10
	v_lshl_add_u32 v54, v10, 2, v182
	ds_read_b32 v58, v11
	ds_read_b32 v59, v54
	v_lshl_add_u64 v[10:11], s[12:13], 0, v[16:17]
	v_lshl_add_u64 v[10:11], v[10:11], 0, v[0:1]
	global_load_dwordx2 v[16:17], v[56:57], off offset:80
	v_lshl_add_u64 v[10:11], v[10:11], 0, v[52:53]
	global_load_dwordx4 v[52:55], v[60:61], off offset:160
	s_waitcnt lgkmcnt(0)
	v_add_f32_e32 v0, v58, v59
	v_fmamk_f32 v0, v0, 0x3c000000, v186
	v_mul_f32_e32 v58, 0x4b800000, v0
	v_cmp_gt_f32_e32 vcc, s35, v0
	s_waitcnt vmcnt(11)
	v_and_b32_e32 v85, 0xffff0000, v64
	v_cndmask_b32_e32 v0, v0, v58, vcc
	global_load_dwordx2 v[80:81], v[56:57], off offset:96
	global_load_dwordx2 v[82:83], v[56:57], off offset:112
	s_nop 0
	global_load_dwordx4 v[56:59], v[60:61], off offset:192
	s_nop 0
	global_load_dwordx4 v[60:63], v[60:61], off offset:224
	v_rsq_f32_e32 v0, v0
	s_nop 0
	v_mul_f32_e32 v84, 0x45800000, v0
	v_cndmask_b32_e32 v0, v0, v84, vcc
	v_pk_mul_f32 v[66:67], v[66:67], v[0:1] op_sel_hi:[1,0]
	v_pk_mul_f32 v[68:69], v[68:69], v[0:1] op_sel_hi:[1,0]
	v_pk_mul_f32 v[70:71], v[70:71], v[0:1] op_sel_hi:[1,0]
	v_pk_mul_f32 v[38:39], v[38:39], v[0:1] op_sel_hi:[1,0]
	v_pk_mul_f32 v[36:37], v[36:37], v[0:1] op_sel_hi:[1,0]
	v_pk_mul_f32 v[34:35], v[34:35], v[0:1] op_sel_hi:[1,0]
	v_lshlrev_b32_e32 v84, 16, v64
	s_waitcnt vmcnt(14)
	v_pk_mul_f32 v[12:13], v[12:13], v[66:67]
	v_and_b32_e32 v67, 0xffff0000, v65
	v_lshlrev_b32_e32 v66, 16, v65
	v_pk_mul_f32 v[14:15], v[14:15], v[68:69]
	s_waitcnt vmcnt(13)
	v_and_b32_e32 v65, 0xffff0000, v72
	v_lshlrev_b32_e32 v64, 16, v72
	s_waitcnt vmcnt(12)
	v_pk_mul_f32 v[30:31], v[30:31], v[70:71]
	v_and_b32_e32 v69, 0xffff0000, v73
	v_lshlrev_b32_e32 v68, 16, v73
	v_pk_mul_f32 v[32:33], v[32:33], v[38:39]
	s_waitcnt vmcnt(11)
	v_and_b32_e32 v39, 0xffff0000, v74
	v_lshlrev_b32_e32 v38, 16, v74
	s_waitcnt vmcnt(10)
	v_pk_mul_f32 v[36:37], v[40:41], v[36:37]
	v_and_b32_e32 v41, 0xffff0000, v75
	v_lshlrev_b32_e32 v40, 16, v75
	v_pk_mul_f32 v[34:35], v[42:43], v[34:35]
	v_pk_mul_f32 v[12:13], v[12:13], v[84:85]
	v_pk_mul_f32 v[14:15], v[14:15], v[66:67]
	v_pk_mul_f32 v[30:31], v[30:31], v[64:65]
	v_pk_mul_f32 v[32:33], v[32:33], v[68:69]
	v_pk_mul_f32 v[36:37], v[36:37], v[38:39]
	v_pk_mul_f32 v[34:35], v[34:35], v[40:41]
	v_cvt_pk_bf16_f32 v12, v12, v13
	v_cvt_pk_bf16_f32 v13, v14, v15
	v_cvt_pk_bf16_f32 v14, v30, v31
	v_cvt_pk_bf16_f32 v15, v32, v33
	v_cvt_pk_bf16_f32 v30, v36, v37
	v_cvt_pk_bf16_f32 v31, v34, v35
	v_and_b32_e32 v233, 63, v172
	v_lshrrev_b32_e32 v232, 6, v172
	v_mul_u32_u24_e32 v232, 0x1200, v232
	v_add_u32_e32 v232, v232, v182
	v_add_u32_e32 v232, 0x3000, v232
	v_and_b32_e32 v244, 31, v233
	v_lshrrev_b32_e32 v245, 5, v233
	v_lshrrev_b32_e32 v246, 3, v233
	v_and_b32_e32 v247, 7, v233
	v_mul_u32_u24_e32 v248, 0x90, v246
	v_lshl_add_u32 v248, v247, 4, v248
	v_add_u32_e32 v233, v248, v232
	v_mul_u32_u24_e32 v248, 0x90, v244
	v_lshl_add_u32 v248, v245, 3, v248
	v_add_u32_e32 v232, v248, v232
	v_sub_u32_e32 v246, v246, v244
	v_lshlrev_b32_e32 v246, 11, v246
	v_lshl_add_u32 v246, v247, 4, v246
	v_lshlrev_b32_e32 v245, 3, v245
	v_sub_u32_e32 v246, v246, v245
	v_ashrrev_i32_e32 v247, 31, v246
	v_lshl_add_u64 v[244:245], v[10:11], 0, v[246:247]
	ds_write_b64 v232, v[12:13]
	ds_write_b64 v232, v[14:15] offset:16
	ds_write_b64 v232, v[30:31] offset:32
	v_pk_mul_f32 v[12:13], v[24:25], v[0:1] op_sel_hi:[1,0]
	v_pk_mul_f32 v[22:23], v[22:23], v[0:1] op_sel_hi:[1,0]
	s_waitcnt vmcnt(9)
	v_and_b32_e32 v43, 0xffff0000, v76
	v_lshlrev_b32_e32 v42, 16, v76
	s_waitcnt vmcnt(8)
	v_pk_mul_f32 v[12:13], v[12:13], v[44:45]
	v_and_b32_e32 v15, 0xffff0000, v77
	v_lshlrev_b32_e32 v14, 16, v77
	v_pk_mul_f32 v[22:23], v[22:23], v[46:47]
	v_pk_mul_f32 v[12:13], v[12:13], v[42:43]
	v_pk_mul_f32 v[14:15], v[22:23], v[14:15]
	v_cvt_pk_bf16_f32 v12, v12, v13
	v_cvt_pk_bf16_f32 v13, v14, v15
	v_pk_mul_f32 v[14:15], v[28:29], v[0:1] op_sel_hi:[1,0]
	ds_write_b64 v232, v[12:13] offset:48
	s_waitcnt vmcnt(7)
	v_and_b32_e32 v13, 0xffff0000, v78
	v_lshlrev_b32_e32 v12, 16, v78
	s_waitcnt vmcnt(6)
	v_pk_mul_f32 v[14:15], v[14:15], v[48:49]
	v_pk_mul_f32 v[22:23], v[26:27], v[0:1] op_sel_hi:[1,0]
	v_pk_mul_f32 v[12:13], v[14:15], v[12:13]
	v_and_b32_e32 v15, 0xffff0000, v79
	v_lshlrev_b32_e32 v14, 16, v79
	v_pk_mul_f32 v[22:23], v[22:23], v[50:51]
	v_cvt_pk_bf16_f32 v12, v12, v13
	v_pk_mul_f32 v[14:15], v[22:23], v[14:15]
	v_pk_mul_f32 v[8:9], v[8:9], v[0:1] op_sel_hi:[1,0]
	v_cvt_pk_bf16_f32 v13, v14, v15
	v_pk_mul_f32 v[14:15], v[20:21], v[0:1] op_sel_hi:[1,0]
	ds_write_b64 v232, v[12:13] offset:64
	s_waitcnt vmcnt(5)
	v_and_b32_e32 v13, 0xffff0000, v16
	v_lshlrev_b32_e32 v12, 16, v16
	s_waitcnt vmcnt(4)
	v_pk_mul_f32 v[14:15], v[14:15], v[52:53]
	v_pk_mul_f32 v[6:7], v[6:7], v[0:1] op_sel_hi:[1,0]
	v_pk_mul_f32 v[12:13], v[14:15], v[12:13]
	v_and_b32_e32 v15, 0xffff0000, v17
	v_lshlrev_b32_e32 v14, 16, v17
	v_pk_mul_f32 v[16:17], v[18:19], v[0:1] op_sel_hi:[1,0]
	v_cvt_pk_bf16_f32 v12, v12, v13
	v_pk_mul_f32 v[16:17], v[16:17], v[54:55]
	s_waitcnt vmcnt(1)
	v_pk_mul_f32 v[8:9], v[8:9], v[56:57]
	v_pk_mul_f32 v[14:15], v[16:17], v[14:15]
	v_pk_mul_f32 v[6:7], v[6:7], v[58:59]
	v_cvt_pk_bf16_f32 v13, v14, v15
	ds_write_b64 v232, v[12:13] offset:80
	v_and_b32_e32 v13, 0xffff0000, v80
	v_lshlrev_b32_e32 v12, 16, v80
	v_pk_mul_f32 v[8:9], v[8:9], v[12:13]
	v_and_b32_e32 v13, 0xffff0000, v81
	v_lshlrev_b32_e32 v12, 16, v81
	v_pk_mul_f32 v[6:7], v[6:7], v[12:13]
	v_pk_mul_f32 v[4:5], v[4:5], v[0:1] op_sel_hi:[1,0]
	v_cvt_pk_bf16_f32 v8, v8, v9
	v_cvt_pk_bf16_f32 v9, v6, v7
	v_and_b32_e32 v7, 0xffff0000, v82
	v_lshlrev_b32_e32 v6, 16, v82
	s_waitcnt vmcnt(0)
	v_pk_mul_f32 v[4:5], v[4:5], v[60:61]
	v_pk_mul_f32 v[2:3], v[2:3], v[0:1] op_sel_hi:[1,0]
	v_pk_mul_f32 v[4:5], v[4:5], v[6:7]
	v_and_b32_e32 v7, 0xffff0000, v83
	v_lshlrev_b32_e32 v6, 16, v83
	v_pk_mul_f32 v[2:3], v[2:3], v[62:63]
	v_cvt_pk_bf16_f32 v4, v4, v5
	v_pk_mul_f32 v[2:3], v[2:3], v[6:7]
	ds_write_b64 v232, v[8:9] offset:96
	v_cvt_pk_bf16_f32 v5, v2, v3
	ds_write_b64 v232, v[4:5] offset:112
	s_waitcnt lgkmcnt(0)
	ds_read_b128 v[200:203], v233
	ds_read_b128 v[204:207], v233 offset:1152
	ds_read_b128 v[208:211], v233 offset:2304
	ds_read_b128 v[212:215], v233 offset:3456
	v_mov_b32_e32 v246, 0x4000
	v_mov_b32_e32 v247, 0
	s_waitcnt lgkmcnt(3)
	global_store_dwordx4 v[244:245], v[200:203], off
	v_lshl_add_u64 v[244:245], v[244:245], 0, v[246:247]
	s_waitcnt lgkmcnt(2)
	global_store_dwordx4 v[244:245], v[204:207], off
	v_lshl_add_u64 v[244:245], v[244:245], 0, v[246:247]
	s_waitcnt lgkmcnt(1)
	global_store_dwordx4 v[244:245], v[208:211], off
	v_lshl_add_u64 v[244:245], v[244:245], 0, v[246:247]
	s_waitcnt lgkmcnt(0)
	global_store_dwordx4 v[244:245], v[212:215], off
